# c8 + chain steps (phase 3, 4a): all LDS operand reads hoisted ahead of the 16 f32 MFMAs with counted lgkmcnt
# speedup vs baseline: 1.0009x; 1.0009x over previous
.LBB0_801:
	s_andn2_b64 vcc, exec, s[0:1]
	s_cbranch_vccnz .LBB0_776
	s_mul_hi_u32 s0, s96, 0x24924925
	s_sub_i32 s1, s96, s0
	s_lshr_b32 s1, s1, 1
	s_add_i32 s1, s1, s0
	s_lshr_b32 s0, s1, 2
	s_mul_i32 s0, s0, 0x23000
	v_subrev_u32_e32 v0, s0, v60
	v_subrev_u32_e32 v39, s0, v56
	v_add_u32_e32 v0, s95, v0
	v_add3_u32 v39, v10, s95, v39
	s_bitcmp0_b32 s96, 0
	v_add_u32_e32 v39, 0x4000, v39
	s_cselect_b32 s1, 0x23000, s89
	v_lshlrev_b32_e32 v73, 2, v11
	v_add3_u32 v41, s1, v54, v73
	v_subrev_u32_e32 v70, s0, v59
	v_subrev_u32_e32 v71, s0, v58
	v_subrev_u32_e32 v72, s0, v57
	v_add_u32_e32 v70, s95, v70
	v_add_u32_e32 v71, s95, v71
	v_add_u32_e32 v72, s95, v72
	ds_read_b128 v[0:3], v0
	ds_read2_b32 v[62:63], v41 offset1:17
	ds_read2_b32 v[46:47], v39 offset1:16
	ds_read2_b32 v[48:49], v39 offset0:32 offset1:48
	ds_read2_b32 v[74:75], v41 offset0:34 offset1:51
	ds_read_b128 v[78:81], v70
	ds_read2_b32 v[66:67], v41 offset0:68 offset1:85
	ds_read2_b32 v[76:77], v41 offset0:102 offset1:119
	ds_read_b128 v[82:85], v71
	ds_read2_b32 v[86:87], v41 offset0:136 offset1:153
	ds_read2_b32 v[88:89], v41 offset0:170 offset1:187
	ds_read_b128 v[90:93], v72
	ds_read2_b32 v[94:95], v41 offset0:204 offset1:221
	ds_read2_b32 v[96:97], v41 offset0:238 offset1:255
	s_cselect_b32 s0, s89, 0x23000
	v_or_b32_e32 v73, s0, v73
	s_add_i32 s0, s96, 1
	v_add_u32_e32 v73, v73, v55
	s_cmp_ge_u32 s0, s30
	s_waitcnt lgkmcnt(10)
	v_mfma_f32_16x16x4_f32 v[46:49], v0, v62, v[46:49]
	v_mfma_f32_16x16x4_f32 v[98:101], v1, v63, 0
	s_waitcnt lgkmcnt(9)
	v_mfma_f32_16x16x4_f32 v[46:49], v2, v74, v[46:49]
	v_mfma_f32_16x16x4_f32 v[98:101], v3, v75, v[98:101]
	s_waitcnt lgkmcnt(7)
	v_mfma_f32_16x16x4_f32 v[46:49], v78, v66, v[46:49]
	v_mfma_f32_16x16x4_f32 v[98:101], v79, v67, v[98:101]
	s_waitcnt lgkmcnt(6)
	v_mfma_f32_16x16x4_f32 v[46:49], v80, v76, v[46:49]
	v_mfma_f32_16x16x4_f32 v[98:101], v81, v77, v[98:101]
	s_waitcnt lgkmcnt(4)
	v_mfma_f32_16x16x4_f32 v[46:49], v82, v86, v[46:49]
	v_mfma_f32_16x16x4_f32 v[98:101], v83, v87, v[98:101]
	s_waitcnt lgkmcnt(3)
	v_mfma_f32_16x16x4_f32 v[46:49], v84, v88, v[46:49]
	v_mfma_f32_16x16x4_f32 v[98:101], v85, v89, v[98:101]
	s_waitcnt lgkmcnt(1)
	v_mfma_f32_16x16x4_f32 v[46:49], v90, v94, v[46:49]
	v_mfma_f32_16x16x4_f32 v[98:101], v91, v95, v[98:101]
	s_waitcnt lgkmcnt(0)
	v_mfma_f32_16x16x4_f32 v[46:49], v92, v96, v[46:49]
	v_mfma_f32_16x16x4_f32 v[98:101], v93, v97, v[98:101]
	s_nop 9
	v_pk_add_f32 v[2:3], v[48:49], v[100:101]
	v_pk_add_f32 v[0:1], v[46:47], v[98:99]
	ds_write2_b32 v73, v0, v1 offset1:17
	ds_write2_b32 v73, v2, v3 offset0:34 offset1:51
	s_cbranch_scc1 .LBB0_775
	v_lshl_add_u64 v[64:65], s[26:27], 0, v[36:37]
	v_lshl_add_u64 v[46:47], s[26:27], 0, v[30:31]
	v_lshl_add_u64 v[48:49], s[26:27], 0, v[32:33]
	v_lshl_add_u64 v[62:63], s[26:27], 0, v[34:35]
	global_store_dword v[64:65], v0, off
	global_store_dword v[62:63], v1, off
	global_store_dword v[48:49], v2, off
	global_store_dword v[46:47], v3, off
	s_branch .LBB0_775

.LBB0_1076:
	s_and_b64 vcc, exec, s[0:1]
	s_cbranch_vccz .LBB0_1053
	s_mul_hi_u32 s0, s25, 0x24924925
	s_sub_i32 s1, s25, s0
	s_lshr_b32 s1, s1, 1
	s_add_i32 s1, s1, s0
	s_lshr_b32 s0, s1, 2
	s_mul_i32 s0, s0, 0x23000
	v_subrev_u32_e32 v2, s0, v73
	v_add_u32_e32 v82, s16, v69
	v_add_u32_e32 v2, v82, v2
	v_subrev_u32_e32 v0, s0, v66
	v_subrev_u32_e32 v51, s0, v68
	s_add_i32 s1, s24, -6
	v_subrev_u32_e32 v50, s0, v67
	s_bitcmp0_b32 s1, 0
	v_add_u32_e32 v51, s16, v51
	v_add_u32_e32 v0, s16, v0
	v_add_u32_e32 v50, s16, v50
	s_cselect_b32 s1, 0x23000, s82
	v_lshlrev_b32_e32 v119, 2, v56
	v_add3_u32 v83, s1, v61, v119
	v_subrev_u32_e32 v116, s0, v72
	v_subrev_u32_e32 v117, s0, v71
	v_subrev_u32_e32 v118, s0, v70
	v_add_u32_e32 v116, v82, v116
	v_add_u32_e32 v117, v82, v117
	v_add_u32_e32 v118, v82, v118
	ds_read_b128 v[2:5], v2
	ds_read2_b32 v[120:121], v83 offset1:17
	ds_read_b32 v74, v51
	ds_read_b32 v75, v50
	ds_read2_b32 v[76:77], v0 offset1:16
	ds_read2_b32 v[96:97], v83 offset0:34 offset1:51
	ds_read_b128 v[84:87], v116
	ds_read2_b32 v[98:99], v83 offset0:68 offset1:85
	ds_read2_b32 v[102:103], v83 offset0:102 offset1:119
	ds_read_b128 v[88:91], v117
	ds_read2_b32 v[104:105], v83 offset0:136 offset1:153
	ds_read2_b32 v[106:107], v83 offset0:170 offset1:187
	ds_read_b128 v[92:95], v118
	ds_read2_b32 v[108:109], v83 offset0:204 offset1:221
	ds_read2_b32 v[110:111], v83 offset0:238 offset1:255
	s_cselect_b32 s0, s82, 0x23000
	v_or_b32_e32 v0, s0, v119
	v_add_u32_e32 v0, v0, v55
	v_lshl_add_u64 v[78:79], s[4:5], 0, v[48:49]
	v_lshl_add_u64 v[50:51], s[4:5], 0, v[42:43]
	s_waitcnt lgkmcnt(10)
	v_mfma_f32_16x16x4_f32 v[74:77], v2, v120, v[74:77]
	v_mfma_f32_16x16x4_f32 v[112:115], v3, v121, 0
	s_waitcnt lgkmcnt(9)
	v_mfma_f32_16x16x4_f32 v[74:77], v4, v96, v[74:77]
	v_mfma_f32_16x16x4_f32 v[112:115], v5, v97, v[112:115]
	s_waitcnt lgkmcnt(7)
	v_mfma_f32_16x16x4_f32 v[74:77], v84, v98, v[74:77]
	v_mfma_f32_16x16x4_f32 v[112:115], v85, v99, v[112:115]
	s_waitcnt lgkmcnt(6)
	v_mfma_f32_16x16x4_f32 v[74:77], v86, v102, v[74:77]
	v_mfma_f32_16x16x4_f32 v[112:115], v87, v103, v[112:115]
	s_waitcnt lgkmcnt(4)
	v_mfma_f32_16x16x4_f32 v[74:77], v88, v104, v[74:77]
	v_mfma_f32_16x16x4_f32 v[112:115], v89, v105, v[112:115]
	s_waitcnt lgkmcnt(3)
	v_mfma_f32_16x16x4_f32 v[74:77], v90, v106, v[74:77]
	v_mfma_f32_16x16x4_f32 v[112:115], v91, v107, v[112:115]
	s_waitcnt lgkmcnt(1)
	v_mfma_f32_16x16x4_f32 v[74:77], v92, v108, v[74:77]
	v_mfma_f32_16x16x4_f32 v[112:115], v93, v109, v[112:115]
	s_waitcnt lgkmcnt(0)
	v_mfma_f32_16x16x4_f32 v[74:77], v94, v110, v[74:77]
	v_mfma_f32_16x16x4_f32 v[112:115], v95, v111, v[112:115]
	s_nop 9
	v_pk_add_f32 v[2:3], v[74:75], v[112:113]
	v_pk_add_f32 v[4:5], v[76:77], v[114:115]
	ds_write2_b32 v0, v2, v3 offset1:17
	ds_write2_b32 v0, v4, v5 offset0:34 offset1:51
	v_lshl_add_u64 v[74:75], s[4:5], 0, v[44:45]
	v_lshl_add_u64 v[76:77], s[4:5], 0, v[46:47]
	global_store_dword v[78:79], v2, off
	global_store_dword v[76:77], v3, off
	global_store_dword v[74:75], v4, off
	global_store_dword v[50:51], v5, off
	s_waitcnt lgkmcnt(0)
	s_branch .LBB0_1053
